# instruction selection (sec 7.5): softmax row sums no longer start from an explicit 0 + p add (2 fewer VALU per attention tile)
# baseline (speedup 1.0000x reference)
; #define LAS __attribute__((address_space(3)))
; __device__ __forceinline__ unsigned cvt_pk_bf16(float lo, float hi) { unsigned r; asm volatile("v_cvt_pk_bf16_f32 %0, %1, %2" : "=v"(r) : "v"(lo), "v"(hi)); return r; }
; __device__ __forceinline__ void attn_item(LAS unsigned char* lds, const bf16_t* z, const float* kmean, bf16_t* cat, int b, int h, int j) {
;     ...
;                 float ls = 0.f; float pv[4][4];
; #pragma unroll
;                 for (int ks = 0; ks < 4; ++ks)
; #pragma unroll
;                     for (int i = 0; i < 4; ++i) { const float pp = __builtin_amdgcn_exp2f(__builtin_fmaf(s[ks][qg][i], SC, sub)); pv[ks][i] = pp; ls += pp; }
;                 lrun[qg] = lrun[qg] * alpha + ls;
;                 if (__ballot(alpha != 1.0f) != 0ull) {
; #pragma unroll
;                     for (int ds = 0; ds < 4; ++ds) o[ds][qg] = o[ds][qg] * alpha;
;                 }
; #pragma unroll
;                 for (int k2 = 0; k2 < 2; ++k2) { const u32x4 w = (u32x4){cvt_pk_bf16(pv[2 * k2][0], pv[2 * k2][1]), cvt_pk_bf16(pv[2 * k2][2], pv[2 * k2][3]),
;                                                                      cvt_pk_bf16(pv[2 * k2 + 1][0], pv[2 * k2 + 1][1]), cvt_pk_bf16(pv[2 * k2 + 1][2], pv[2 * k2 + 1][3])};
;                     Pf[qg][k2] = __builtin_bit_cast(bf16x8, w); }
;             }
; #pragma unroll
;             for (int ds = 0; ds < 4; ++ds)
; #pragma unroll
;                 for (int k2 = 0; k2 < 2; ++k2) {
;                     const u32x2 lo = *(const LAS u32x2*)(Vt + (ds * 16 + lq) * 72 + k2 * 32 + quad * 4), hi = *(const LAS u32x2*)(Vt + (ds * 16 + lq) * 72 + k2 * 32 + 16 + quad * 4);
;                     const bf16x8 vf = __builtin_bit_cast(bf16x8, (u32x4){lo.x, lo.y, hi.x, hi.y});
; #pragma unroll
;                     for (int qg = 0; qg < 2; ++qg) o[ds][qg] = __builtin_amdgcn_mfma_f32_16x16x32_bf16(vf, Pf[qg][k2], o[ds][qg], 0, 0, 0);
.LBB0_1605:
	v_add_f32_e32 v111, v144, v145
	v_add_f32_e32 v111, v146, v111
	v_add_f32_e32 v111, v147, v111
	v_add_f32_e32 v111, v148, v111
	v_add_f32_e32 v111, v149, v111
	v_add_f32_e32 v111, v150, v111
	v_add_f32_e32 v111, v151, v111
	v_add_f32_e32 v90, v90, v111
	v_add_f32_e32 v90, v91, v90
	v_mul_f32_e32 v91, 0xbe38aa3b, v115
	v_cndmask_b32_e64 v91, v237, v91, s[8:9]
	v_fmamk_f32 v78, v78, 0x3e38aa3b, v91
	v_exp_f32_e32 v78, v78
	v_fmamk_f32 v79, v79, 0x3e38aa3b, v91
	v_exp_f32_e32 v79, v79
	v_fmamk_f32 v80, v80, 0x3e38aa3b, v91
	v_add_f32_e32 v90, v152, v90
	v_exp_f32_e32 v80, v80
	v_fmamk_f32 v81, v81, 0x3e38aa3b, v91
	v_add_f32_e32 v90, v93, v90
	v_exp_f32_e32 v81, v81
	v_fmamk_f32 v62, v62, 0x3e38aa3b, v91
	v_add_f32_e32 v90, v94, v90
	v_exp_f32_e32 v94, v62
	v_add_f32_e32 v93, v78, v79
	v_add_f32_e32 v93, v80, v93
	v_add_f32_e32 v93, v81, v93
	v_fmamk_f32 v63, v63, 0x3e38aa3b, v91
	v_add_f32_e32 v62, v94, v93
	v_exp_f32_e32 v93, v63
	v_fmamk_f32 v63, v64, 0x3e38aa3b, v91
	v_add_f32_e32 v90, v95, v90
	v_exp_f32_e32 v95, v63
	v_fmamk_f32 v63, v65, 0x3e38aa3b, v91
	v_exp_f32_e32 v65, v63
	v_fmamk_f32 v58, v58, 0x3e38aa3b, v91
	v_exp_f32_e32 v58, v58
	v_fmamk_f32 v59, v59, 0x3e38aa3b, v91
	v_add_f32_e32 v62, v93, v62
	v_exp_f32_e32 v59, v59
	v_fmamk_f32 v60, v60, 0x3e38aa3b, v91
	v_add_f32_e32 v62, v95, v62
	v_exp_f32_e32 v60, v60
	v_fmamk_f32 v61, v61, 0x3e38aa3b, v91
	v_add_f32_e32 v62, v65, v62
	v_exp_f32_e32 v61, v61
	v_fmamk_f32 v63, v74, 0x3e38aa3b, v91
	v_add_f32_e32 v62, v58, v62
	v_exp_f32_e32 v74, v63
	v_fmamk_f32 v63, v75, 0x3e38aa3b, v91
	v_add_f32_e32 v62, v59, v62
	v_exp_f32_e32 v75, v63
	v_fmamk_f32 v63, v76, 0x3e38aa3b, v91
	v_add_f32_e32 v62, v60, v62
	v_exp_f32_e32 v76, v63
	v_fmac_f32_e32 v91, 0x3e38aa3b, v77
	v_add_f32_e32 v62, v61, v62
	v_exp_f32_e32 v77, v91
	v_add_f32_e32 v62, v74, v62
	v_add_f32_e32 v62, v75, v62
	v_add_f32_e32 v62, v76, v62
	v_add_f32_e32 v91, v77, v62
	v_cvt_pk_bf16_f32 v62, v78, v79
	v_cvt_pk_bf16_f32 v63, v80, v81
	v_cvt_pk_bf16_f32 v64, v94, v93
	v_cvt_pk_bf16_f32 v65, v95, v65
	v_cvt_pk_bf16_f32 v58, v58, v59
	v_cvt_pk_bf16_f32 v59, v60, v61
	v_cvt_pk_bf16_f32 v60, v74, v75
	s_waitcnt lgkmcnt(0)
	v_cvt_pk_bf16_f32 v61, v76, v77
	v_mfma_f32_16x16x32_bf16 v[4:7], v[154:157], v[86:89], v[4:7]
	v_add_f32_e32 v90, v96, v90
	v_add_f32_e32 v90, v97, v90
	v_fmac_f32_e32 v90, v108, v110
	v_mfma_f32_16x16x32_bf16 v[0:3], v[154:157], v[62:65], v[0:3]
	v_fmac_f32_e32 v91, v109, v92
	v_mov_b64_e32 v[108:109], v[90:91]
	v_mfma_f32_16x16x32_bf16 v[4:7], v[158:161], v[82:85], v[4:7]
	v_mov_b64_e32 v[110:111], v[114:115]
	v_mfma_f32_16x16x32_bf16 v[0:3], v[158:161], v[58:61], v[0:3]
	v_mfma_f32_16x16x32_bf16 v[30:33], v[162:165], v[86:89], v[30:33]
	v_mfma_f32_16x16x32_bf16 v[26:29], v[162:165], v[62:65], v[26:29]
	v_mfma_f32_16x16x32_bf16 v[30:33], v[166:169], v[82:85], v[30:33]
	v_mfma_f32_16x16x32_bf16 v[26:29], v[166:169], v[58:61], v[26:29]
	v_mfma_f32_16x16x32_bf16 v[38:41], v[170:173], v[86:89], v[38:41]
	v_mfma_f32_16x16x32_bf16 v[34:37], v[170:173], v[62:65], v[34:37]
	v_mfma_f32_16x16x32_bf16 v[38:41], v[174:177], v[82:85], v[38:41]
	v_mfma_f32_16x16x32_bf16 v[34:37], v[174:177], v[58:61], v[34:37]
	v_mfma_f32_16x16x32_bf16 v[42:45], v[178:181], v[62:65], v[42:45]
	v_mfma_f32_16x16x32_bf16 v[46:49], v[178:181], v[86:89], v[46:49]
	v_mfma_f32_16x16x32_bf16 v[46:49], v[182:185], v[82:85], v[46:49]
	v_mfma_f32_16x16x32_bf16 v[42:45], v[182:185], v[58:61], v[42:45]
